# RSCAN: XOR-swizzled LDS layout of P tile removes 4-way bank conflict on ds_read_b128; plus prefetch distance 2
# speedup vs baseline: 1.0287x; 1.0287x over previous
; #define LAS __attribute__((address_space(3)))
; __device__ __forceinline__ int opaque_tid_w(int wid_s) { unsigned z = 0u; asm volatile("" : "+v"(z)); int t = (wid_s << 6) | (int)__builtin_amdgcn_mbcnt_hi(~0u, __builtin_amdgcn_mbcnt_lo(~0u, z)); return t; }
; __device__ __forceinline__ void rk_scan(LAS unsigned char* lds, unsigned char* ws, int bid, int wid_s) {
;     ...
;   const int tid = opaque_tid_w(wid_s), wid = wid_s, lane = tid & 63, h = bid >> 2, i0 = (bid & 3) * 16, i = lane >> 2, q = lane & 3;
;   const float* Pg = (const float*)(ws + A_RP) + (size_t)h * RK_NC * 4096; float* Bg = (float*)(ws + A_RB) + (size_t)h * RK_NC * 4096;
;   LAS float* PL = (LAS float*)lds; LAS float* SX = (LAS float*)(lds + 32768);
;   f32x2 S[8];
;   float zf = 0.f; asm volatile("" : "+v"(zf));
; #pragma unroll
;   for (int j = 0; j < 8; ++j) S[j] = (f32x2){zf, zf};
;   f32x4 p0 = *(const f32x4*)(Pg + tid * 8), p1 = *(const f32x4*)(Pg + tid * 8 + 4);
;   *(LAS f32x4*)(PL + tid * 8) = p0; *(LAS f32x4*)(PL + tid * 8 + 4) = p1;
;   const size_t brow = (size_t)(i0 + i) * 64 + 8 * wid;
;   f32x4 bn0 = *(const f32x4*)(Bg + brow), bn1 = *(const f32x4*)(Bg + brow + 4);
;   asm volatile("s_waitcnt vmcnt(0) lgkmcnt(0)" ::: "memory"); __builtin_amdgcn_s_barrier(); asm volatile("" ::: "memory");
;   for (int c = 0; c < RK_NC; ++c) {
;     const LAS float* pl = PL + (c & 1) * 4096 + 8 * wid + q * 16 * 64;
;     const f32x4 b0 = bn0, b1 = bn1;
;     if (c + 1 < RK_NC) { p0 = *(const f32x4*)(Pg + (size_t)(c + 1) * 4096 + tid * 8); p1 = *(const f32x4*)(Pg + (size_t)(c + 1) * 4096 + tid * 8 + 4);
;       bn0 = *(const f32x4*)(Bg + (size_t)(c + 1) * 4096 + brow); bn1 = *(const f32x4*)(Bg + (size_t)(c + 1) * 4096 + brow + 4); }
;     f32x2 o0 = (f32x2){zf, zf}, o1 = o0, o2 = o0, o3 = o0;
;     f32x4 PA[2][4], PB[2][4];
; #pragma unroll
;     for (int j = 0; j < 4; ++j) { PA[0][j] = *(const LAS f32x4*)(pl + j * 64); PB[0][j] = *(const LAS f32x4*)(pl + j * 64 + 4); }
.LBB0_25:
	s_bitcmp1_b32 s93, 0
	s_cselect_b64 s[0:1], -1, 0
	s_and_b64 vcc, exec, s[0:1]
	s_cbranch_vccnz .LBB0_24
	v_readlane_b32 s0, v254, 0
	s_mov_b32 s36, s0
	s_lshr_b32 s0, s93, 1
	s_mul_hi_u32 s8, s0, 56
	s_mul_i32 s9, s0, 56
	s_getpc_b64 s[0:1]
	s_add_u32 s0, s0, PROG@rel32@lo+4
	s_addc_u32 s1, s1, PROG@rel32@hi+12
	s_add_u32 s0, s0, s9
	s_addc_u32 s1, s1, s8
	s_getpc_b64 s[4:5]
	s_add_u32 s4, s4, PROG@rel32@lo+52
	s_addc_u32 s5, s5, PROG@rel32@hi+60
	s_add_u32 s4, s4, s9
	s_addc_u32 s5, s5, s8
	v_readlane_b32 s84, v254, 1
	v_readlane_b32 s22, v254, 5
	v_readlane_b32 s86, v254, 3
	s_getpc_b64 s[6:7]
	s_add_u32 s6, s6, PROG@rel32@lo+36
	s_addc_u32 s7, s7, PROG@rel32@hi+44
	v_readlane_b32 s85, v254, 2
	v_readlane_b32 s23, v254, 6
	s_mov_b32 s29, s59
	s_mov_b32 s44, s86
	s_add_u32 s6, s6, s9
	s_addc_u32 s7, s7, s8
	s_load_dwordx8 s[8:15], s[0:1], 0x0
	s_load_dwordx2 s[48:49], s[4:5], 0x0
	s_load_dwordx4 s[16:19], s[6:7], 0x0
	v_readlane_b32 s87, v254, 4
	s_add_i32 s82, s29, 0
	s_add_i32 s0, s82, 0x20000
	s_waitcnt lgkmcnt(0)
	v_writelane_b32 v254, s16, 25
	s_nop 1
	v_writelane_b32 v254, s17, 26
	v_writelane_b32 v254, s18, 27
	v_writelane_b32 v254, s19, 28
	v_writelane_b32 v254, s22, 29
	s_nop 1
	v_writelane_b32 v254, s23, 30
	v_writelane_b32 v254, s22, 31
	s_nop 1
	v_writelane_b32 v254, s23, 32
	v_writelane_b32 v254, s0, 33
	v_writelane_b32 v254, s8, 34
	s_cmp_lt_i32 s8, 7
	s_mov_b64 s[0:1], -1
	v_writelane_b32 v254, s9, 35
	v_writelane_b32 v254, s10, 36
	v_writelane_b32 v254, s11, 37
	v_writelane_b32 v254, s12, 38
	v_writelane_b32 v254, s13, 39
	v_writelane_b32 v254, s14, 40
	v_writelane_b32 v254, s15, 41
	s_cbranch_scc1 .LBB0_131
	v_readlane_b32 s4, v254, 34
	s_cmp_lt_i32 s4, 10
	v_readlane_b32 s5, v254, 35
	v_readlane_b32 s6, v254, 36
	v_readlane_b32 s7, v254, 37
	v_readlane_b32 s8, v254, 38
	v_readlane_b32 s9, v254, 39
	v_readlane_b32 s10, v254, 40
	v_readlane_b32 s11, v254, 41
	s_cbranch_scc1 .LBB0_76
	v_readlane_b32 s4, v254, 34
	s_cmp_lt_i32 s4, 11
	v_readlane_b32 s5, v254, 35
	v_readlane_b32 s6, v254, 36
	v_readlane_b32 s7, v254, 37
	v_readlane_b32 s8, v254, 38
	v_readlane_b32 s9, v254, 39
	v_readlane_b32 s10, v254, 40
	v_readlane_b32 s11, v254, 41
	s_cbranch_scc1 .LBB0_52
	v_readlane_b32 s4, v254, 34
	s_cmp_lt_i32 s4, 12
	v_readlane_b32 s5, v254, 35
	v_readlane_b32 s6, v254, 36
	v_readlane_b32 s7, v254, 37
	v_readlane_b32 s8, v254, 38
	v_readlane_b32 s9, v254, 39
	v_readlane_b32 s10, v254, 40
	v_readlane_b32 s11, v254, 41
	s_cbranch_scc1 .LBB0_40
	v_readlane_b32 s4, v254, 34
	s_cmp_eq_u32 s4, 12
	v_readlane_b32 s5, v254, 35
	v_readlane_b32 s6, v254, 36
	v_readlane_b32 s7, v254, 37
	v_readlane_b32 s8, v254, 38
	v_readlane_b32 s9, v254, 39
	v_readlane_b32 s10, v254, 40
	v_readlane_b32 s11, v254, 41
	s_cbranch_scc0 .LBB0_39
	s_cmp_gt_i32 s36, 63
	s_cbranch_scc1 .LBB0_39
	v_mov_b32_e32 v0, v1
	s_ashr_i32 s0, s36, 2
	v_mbcnt_lo_u32_b32 v0, -1, v0
	v_mbcnt_hi_u32_b32 v0, -1, v0
	s_ashr_i32 s1, s0, 31
	v_readlane_b32 s4, v254, 7
	s_lshl_b32 s6, s36, 4
	s_mov_b32 s7, 0xde00000
	v_lshl_or_b32 v10, v0, 3, s4
	s_lshl_b64 s[4:5], s[0:1], 21
	s_add_u32 s0, s84, s4
	v_ashrrev_i32_e32 v11, 31, v10
	s_addc_u32 s1, s85, s5
	v_lshl_add_u64 v[46:47], v[10:11], 2, s[0:1]
	s_mov_b64 s[8:9], 0xde00000
	v_add_co_u32_e32 v2, vcc, s7, v46
	v_mov_b32_e32 v44, v1
	v_lshl_add_u64 v[6:7], v[46:47], 0, s[8:9]
	v_addc_co_u32_e32 v3, vcc, 0, v47, vcc
	global_load_dwordx4 v[2:5], v[2:3], off
	s_nop 0
	global_load_dwordx4 v[6:9], v[6:7], off offset:16
	v_bfe_u32 v19, v0, 2, 4
	v_and_b32_e32 v18, 3, v0
	v_and_or_b32 v0, s6, 48, v19
	v_readlane_b32 s6, v254, 20
	v_lshl_add_u32 v57, v10, 2, s82
	v_readlane_b32 s100, v254, 12
	s_lshr_b32 s100, s100, 1
	s_lshl_b32 s100, s100, 5
	v_xor_b32_e32 v57, s100, v57
	v_lshlrev_b32_e32 v0, 8, v0
	v_readlane_b32 s7, v254, 21
	s_mov_b32 s7, s59
	v_mov_b32_e32 v20, s82
	s_add_i32 s8, s82, s6
	v_lshl_add_u32 v55, v18, 12, s8
	v_lshlrev_b32_e32 v146, 5, v18
	v_xor_b32_e32 v55, v55, v146
	v_mov_b32_e32 v45, v44
	v_mul_u32_u24_e32 v53, 0x110, v19
	s_movk_i32 s9, 0x1000
	v_mov_b32_e32 v38, v44
	v_mov_b32_e32 v64, v44
	v_mov_b32_e32 v40, v44
	v_mov_b32_e32 v62, v44
	v_mov_b32_e32 v26, v44
	v_mov_b32_e32 v58, v44
	v_mov_b32_e32 v28, v44
	v_mov_b32_e32 v54, v44
	v_mov_b32_e32 v52, v44
	v_mov_b32_e32 v22, v44
	v_mov_b32_e32 v60, v44
	v_mov_b32_e32 v24, v44
	v_mov_b32_e32 v56, v44
	s_waitcnt vmcnt(1)
	ds_write_b128 v57, v[2:5]
	s_waitcnt vmcnt(0)
	ds_write_b128 v57, v[6:9] offset:16
	v_lshl_add_u64 v[2:3], s[0:1], 0, v[0:1]
	v_lshl_add_u64 v[2:3], v[2:3], 0, s[6:7]
	s_mov_b64 s[0:1], 0xbe00000
	v_lshl_add_u64 v[42:43], v[2:3], 0, s[0:1]
	s_mov_b32 s0, 0xbe00000
	v_add_co_u32_e32 v2, vcc, s0, v2
	s_mov_b32 s0, s6
	s_nop 0
	v_addc_co_u32_e32 v3, vcc, 0, v3, vcc
	global_load_dwordx4 v[10:13], v[2:3], off
	global_load_dwordx4 v[14:17], v[42:43], off offset:16
	v_writelane_b32 v254, s0, 20
	s_movk_i32 s6, 0x110
	v_mad_u32_u24 v2, v19, s6, v20
	v_writelane_b32 v254, s1, 21
	s_waitcnt vmcnt(0) lgkmcnt(0)
	s_barrier
	v_readlane_b32 s6, v254, 15
	s_add_u32 s6, s84, s6
	s_addc_u32 s7, s85, 0
	s_add_u32 s4, s6, s4
	v_lshlrev_b32_e32 v3, 6, v18
	s_addc_u32 s5, s7, s5
	v_cmp_eq_u32_e64 s[0:1], 0, v18
	v_lshl_add_u64 v[48:49], s[4:5], 0, v[0:1]
	s_mov_b64 s[4:5], 0
	v_add_u32_e32 v59, v2, v3
	v_mov_b32_e32 v18, v44
	v_mov_b32_e32 v0, v44
	v_mov_b32_e32 v20, v44
	s_mov_b64 s[6:7], 0xbe04000
	v_lshl_add_u64 v[150:151], v[48:49], 0, s[6:7]
	s_mov_b64 s[6:7], 0xde04000
	v_lshl_add_u64 v[152:153], v[46:47], 0, s[6:7]
	global_load_dwordx4 v[130:133], v[152:153], off
	global_load_dwordx4 v[138:141], v[150:151], off
	global_load_dwordx4 v[134:137], v[152:153], off offset:16
	global_load_dwordx4 v[142:145], v[150:151], off offset:16
	s_branch .LBB0_34

; #define LAS __attribute__((address_space(3)))
; __global__ void __launch_bounds__(512, 2) mega_fwd(KArgs args) {
;   extern __shared__ __attribute__((aligned(16))) unsigned char lds_raw[];
;   LAS unsigned char* lds = (LAS unsigned char*)lds_raw;
;   LAS ull* PT = (LAS ull*)(lds + PT_OFF);
;   const int wid_s = __builtin_amdgcn_readfirstlane((int)threadIdx.x >> 6);
	.amdhsa_kernel _Z8mega_fwd5KArgs
		.amdhsa_group_segment_fixed_size 0
		.amdhsa_private_segment_fixed_size 0
		.amdhsa_kernarg_size 696
		.amdhsa_user_sgpr_count 2
		.amdhsa_user_sgpr_dispatch_ptr 0
		.amdhsa_user_sgpr_queue_ptr 0
		.amdhsa_user_sgpr_kernarg_segment_ptr 1
		.amdhsa_user_sgpr_dispatch_id 0
		.amdhsa_user_sgpr_kernarg_preload_length 0
		.amdhsa_user_sgpr_kernarg_preload_offset 0
		.amdhsa_user_sgpr_private_segment_size 0
		.amdhsa_uses_dynamic_stack 0
		.amdhsa_enable_private_segment 0
		.amdhsa_system_sgpr_workgroup_id_x 1
		.amdhsa_system_sgpr_workgroup_id_y 0
		.amdhsa_system_sgpr_workgroup_id_z 0
		.amdhsa_system_sgpr_workgroup_info 0
		.amdhsa_system_vgpr_workitem_id 2
		.amdhsa_next_free_vgpr 256
		.amdhsa_next_free_sgpr 102
		.amdhsa_accum_offset 256
		.amdhsa_reserve_vcc 1
		.amdhsa_float_round_mode_32 0
		.amdhsa_float_round_mode_16_64 0
		.amdhsa_float_denorm_mode_32 3
		.amdhsa_float_denorm_mode_16_64 3
		.amdhsa_dx10_clamp 1
		.amdhsa_ieee_mode 1
		.amdhsa_fp16_overflow 0
		.amdhsa_tg_split 0
		.amdhsa_exception_fp_ieee_invalid_op 0
		.amdhsa_exception_fp_denorm_src 0
		.amdhsa_exception_fp_ieee_div_zero 0
		.amdhsa_exception_fp_ieee_overflow 0
		.amdhsa_exception_fp_ieee_underflow 0
		.amdhsa_exception_fp_ieee_inexact 0
		.amdhsa_exception_int_div_zero 0
	.end_amdhsa_kernel

; #define LAS __attribute__((address_space(3)))
; __global__ void __launch_bounds__(512, 2) mega_fwd(KArgs args) {
;   extern __shared__ __attribute__((aligned(16))) unsigned char lds_raw[];
;   LAS unsigned char* lds = (LAS unsigned char*)lds_raw;
;   LAS ull* PT = (LAS ull*)(lds + PT_OFF);
;   const int wid_s = __builtin_amdgcn_readfirstlane((int)threadIdx.x >> 6);
amdhsa.kernels:
  - .agpr_count:     0
    .args:
      - .offset:         0
        .size:           440
        .value_kind:     by_value
      - .offset:         440
        .size:           4
        .value_kind:     hidden_block_count_x
      - .offset:         444
        .size:           4
        .value_kind:     hidden_block_count_y
      - .offset:         448
        .size:           4
        .value_kind:     hidden_block_count_z
      - .offset:         452
        .size:           2
        .value_kind:     hidden_group_size_x
      - .offset:         454
        .size:           2
        .value_kind:     hidden_group_size_y
      - .offset:         456
        .size:           2
        .value_kind:     hidden_group_size_z
      - .offset:         458
        .size:           2
        .value_kind:     hidden_remainder_x
      - .offset:         460
        .size:           2
        .value_kind:     hidden_remainder_y
      - .offset:         462
        .size:           2
        .value_kind:     hidden_remainder_z
      - .offset:         480
        .size:           8
        .value_kind:     hidden_global_offset_x
      - .offset:         488
        .size:           8
        .value_kind:     hidden_global_offset_y
      - .offset:         496
        .size:           8
        .value_kind:     hidden_global_offset_z
      - .offset:         504
        .size:           2
        .value_kind:     hidden_grid_dims
      - .offset:         528
        .size:           8
        .value_kind:     hidden_multigrid_sync_arg
      - .offset:         560
        .size:           4
        .value_kind:     hidden_dynamic_lds_size
    .group_segment_fixed_size: 0
    .kernarg_segment_align: 8
    .kernarg_segment_size: 696
    .language:       OpenCL C
    .language_version:
      - 2
      - 0
    .max_flat_workgroup_size: 512
    .name:           _Z8mega_fwd5KArgs
    .private_segment_fixed_size: 0
    .sgpr_count:     108
    .sgpr_spill_count: 136
    .symbol:         _Z8mega_fwd5KArgs.kd
    .uniform_work_group_size: 1
    .uses_dynamic_stack: false
    .vgpr_count:     256
    .vgpr_spill_count: 0
    .wavefront_size: 64
